# GEMM K-loop: six duplicated adjacent lgkmcnt(0) waits removed
# baseline (speedup 1.0000x reference)
; #define PG8_STAGE(bufoff, gbase, voff) do { _Pragma("unroll") for (int _i = 0; _i < 2; ++_i) \
;         __builtin_amdgcn_global_load_lds((const unsigned*)((const char*)(gbase) + (voff)[_i]), (LAS unsigned*)(lds + (bufoff) + ldsw + _i * 8192), 16, 0, 0); } while (0)
; #define PG8_LDA(dst, b, h) do { _Pragma("unroll") for (int m = 0; m < 4; ++m) _Pragma("unroll") for (int k = 0; k < 2; ++k) dst[m][k] = *(const LAS bf16x8*)(lds + PG8_SA(b, h) + aoff + m * 2048 + k * 1024); } while (0)
; #define PG8_LDB(dst, b, h) do { _Pragma("unroll") for (int n = 0; n < 2; ++n) _Pragma("unroll") for (int k = 0; k < 2; ++k) dst[n][k] = *(const LAS bf16x8*)(lds + PG8_SB(b, h) + boff + n * 2048 + k * 1024); } while (0)
; #define PG8_MMA(ai, bj, At, Bt) do { __builtin_amdgcn_s_setprio(1); _Pragma("unroll") for (int m = 0; m < 4; ++m) _Pragma("unroll") for (int n = 0; n < 2; ++n) _Pragma("unroll") for (int k = 0; k < 2; ++k) \
;         acc[ai][bj][m][n] = __builtin_amdgcn_mfma_f32_16x16x32_bf16(Bt[n][k], At[m][k], acc[ai][bj][m][n], 0, 0, 0); __builtin_amdgcn_s_setprio(0); } while (0)
; #define PG8_WAIT_V(n) asm volatile("s_waitcnt vmcnt(" #n ")" ::: "memory")
; #define PG8_WAIT_L(n) asm volatile("s_waitcnt lgkmcnt(" #n ")" ::: "memory")
; template <class Epi>
; __device__ __forceinline__ void gemm_phase(LAS unsigned char* lds, const Gemm g, const StaticOrder& S, const Epi& E) {
;     ...
;         for (int t = 0; t < nt; t += 2) {
;             const bool last = (t == nt - 2);
;             const char* a1 = cA + (size_t)(t + 1) * kstep;
;             const char* a2 = last ? nA : cA + (size_t)(t + 2) * kstep; const char* b2 = last ? nB : cB + (size_t)(t + 2) * kstep;
;             const char* a3 = a2 + kstep; const char* b3 = b2 + kstep;
;             PG8_LDB(B0, 0, 0); PG8_SCHED; PG8_LDA(At, 0, 0); PG8_STAGE(PG8_SA(1, 1), a1 + hstepA, voffA);
;             PG8_WAIT_L(8); PG8_BAR; PG8_WAIT_L(0); PG8_MMA(0, 0, At, B0); PG8_BAR; PG8_SCHED;
;             PG8_LDB(B1, 0, 1); PG8_STAGE(PG8_SB(0, 0), b2, voffB);
;             PG8_BAR; PG8_WAIT_L(0); PG8_MMA(0, 1, At, B1); PG8_BAR;
;             PG8_LDA(At, 0, 1); PG8_STAGE(PG8_SA(0, 0), a2, voffA);
;             PG8_BAR; PG8_WAIT_L(0); PG8_MMA(1, 0, At, B0); PG8_BAR; PG8_SCHED;
;             PG8_STAGE(PG8_SB(0, 1), b2 + hstepB, voffB);
;             PG8_WAIT_V(6); PG8_BAR; PG8_MMA(1, 1, At, B1); PG8_BAR;
.LBB0_302:
	s_add_u32 s10, s46, s64
	s_addc_u32 s11, s47, s65
	s_add_u32 s100, s10, 0x80
	s_addc_u32 s101, s11, 0
	s_add_u32 s10, s10, 0x100
	s_addc_u32 s11, s11, 0
	s_add_u32 s66, vcc_lo, s64
	s_addc_u32 s67, vcc_hi, s65
	s_add_i32 s72, 0, 0x10000
	v_add_u32_e32 v144, s72, v252
	ds_read_b128 v[132:135], v144
	ds_read_b128 v[136:139], v144 offset:1024
	ds_read_b128 v[140:143], v144 offset:2048
	ds_read_b128 v[144:147], v144 offset:3072
	s_cmpk_eq_i32 s64, 0x700
	s_cselect_b32 s69, s61, s11
	s_cselect_b32 s68, s60, s10
	s_cselect_b32 s67, s59, s67
	s_cselect_b32 s66, s58, s66
	s_add_i32 m0, s12, 0xc000
	ds_read_b128 v[148:151], v241
	ds_read_b128 v[152:155], v241 offset:1024
	ds_read_b128 v[156:159], v241 offset:2048
	ds_read_b128 v[160:163], v241 offset:3072
	ds_read_b128 v[164:167], v241 offset:4096
	ds_read_b128 v[168:171], v241 offset:5120
	ds_read_b128 v[172:175], v241 offset:6144
	ds_read_b128 v[192:195], v241 offset:7168
	global_load_lds_dwordx4 v190, s[100:101]
	s_add_i32 m0, s12, 0xe000
	s_nop 0
	global_load_lds_dwordx4 v188, s[100:101]
	s_waitcnt lgkmcnt(8)
	s_barrier
	s_waitcnt lgkmcnt(0)
	v_mfma_f32_16x16x32_bf16 v[124:127], v[132:135], v[148:151], v[124:127]
	v_mfma_f32_16x16x32_bf16 v[120:123], v[140:143], v[148:151], v[120:123]
	v_mfma_f32_16x16x32_bf16 v[116:119], v[132:135], v[156:159], v[116:119]
	v_mfma_f32_16x16x32_bf16 v[112:115], v[140:143], v[156:159], v[112:115]
	v_mfma_f32_16x16x32_bf16 v[108:111], v[132:135], v[164:167], v[108:111]
	v_mfma_f32_16x16x32_bf16 v[104:107], v[140:143], v[164:167], v[104:107]
	v_mfma_f32_16x16x32_bf16 v[100:103], v[132:135], v[172:175], v[100:103]
	v_mfma_f32_16x16x32_bf16 v[96:99], v[140:143], v[172:175], v[96:99]
	v_mfma_f32_16x16x32_bf16 v[124:127], v[136:139], v[152:155], v[124:127]
	v_mfma_f32_16x16x32_bf16 v[120:123], v[144:147], v[152:155], v[120:123]
	v_mfma_f32_16x16x32_bf16 v[116:119], v[136:139], v[160:163], v[116:119]
	v_mfma_f32_16x16x32_bf16 v[112:115], v[144:147], v[160:163], v[112:115]
	v_mfma_f32_16x16x32_bf16 v[108:111], v[136:139], v[168:171], v[108:111]
	v_mfma_f32_16x16x32_bf16 v[104:107], v[144:147], v[168:171], v[104:107]
	v_mfma_f32_16x16x32_bf16 v[100:103], v[136:139], v[192:195], v[100:103]
	v_mfma_f32_16x16x32_bf16 v[96:99], v[144:147], v[192:195], v[96:99]
	s_barrier
	s_add_i32 s40, 0, 0x14000
	s_add_i32 s10, s72, s57
	v_add_u32_e32 v176, s40, v252
	s_mov_b32 m0, s10
	ds_read_b128 v[196:199], v176
	ds_read_b128 v[200:203], v176 offset:1024
	ds_read_b128 v[204:207], v176 offset:2048
	ds_read_b128 v[208:211], v176 offset:3072
	global_load_lds_dwordx4 v182, s[66:67]
	s_add_i32 m0, s10, 0x2000
	s_nop 0
	global_load_lds_dwordx4 v186, s[66:67]
	s_barrier
	s_waitcnt lgkmcnt(0)
	v_mfma_f32_16x16x32_bf16 v[60:63], v[196:199], v[148:151], v[60:63]
	v_mfma_f32_16x16x32_bf16 v[56:59], v[204:207], v[148:151], v[56:59]
	v_mfma_f32_16x16x32_bf16 v[52:55], v[196:199], v[156:159], v[52:55]
	v_mfma_f32_16x16x32_bf16 v[48:51], v[204:207], v[156:159], v[48:51]
	v_mfma_f32_16x16x32_bf16 v[44:47], v[196:199], v[164:167], v[44:47]
	v_mfma_f32_16x16x32_bf16 v[40:43], v[204:207], v[164:167], v[40:43]
	v_mfma_f32_16x16x32_bf16 v[36:39], v[196:199], v[172:175], v[36:39]
	v_mfma_f32_16x16x32_bf16 v[32:35], v[204:207], v[172:175], v[32:35]
	v_mfma_f32_16x16x32_bf16 v[60:63], v[200:203], v[152:155], v[60:63]
	v_mfma_f32_16x16x32_bf16 v[56:59], v[208:211], v[152:155], v[56:59]
	v_mfma_f32_16x16x32_bf16 v[52:55], v[200:203], v[160:163], v[52:55]
	v_mfma_f32_16x16x32_bf16 v[48:51], v[208:211], v[160:163], v[48:51]
	v_mfma_f32_16x16x32_bf16 v[44:47], v[200:203], v[168:171], v[44:47]
	v_mfma_f32_16x16x32_bf16 v[40:43], v[208:211], v[168:171], v[40:43]
	v_mfma_f32_16x16x32_bf16 v[36:39], v[200:203], v[192:195], v[36:39]
	v_mfma_f32_16x16x32_bf16 v[32:35], v[208:211], v[192:195], v[32:35]
	s_mov_b32 m0, s12
	s_barrier
	ds_read_b128 v[148:151], v241 offset:16384
	ds_read_b128 v[152:155], v241 offset:17408
	ds_read_b128 v[156:159], v241 offset:18432
	ds_read_b128 v[160:163], v241 offset:19456
	ds_read_b128 v[164:167], v241 offset:20480
	ds_read_b128 v[168:171], v241 offset:21504
	ds_read_b128 v[172:175], v241 offset:22528
	ds_read_b128 v[192:195], v241 offset:23552
	global_load_lds_dwordx4 v180, s[68:69]
	s_mov_b32 m0, s13
	s_nop 0
	global_load_lds_dwordx4 v184, s[68:69]
	s_barrier
	s_waitcnt lgkmcnt(0)
	v_mfma_f32_16x16x32_bf16 v[92:95], v[132:135], v[148:151], v[92:95]
	v_mfma_f32_16x16x32_bf16 v[88:91], v[140:143], v[148:151], v[88:91]
	v_mfma_f32_16x16x32_bf16 v[84:87], v[132:135], v[156:159], v[84:87]
	v_mfma_f32_16x16x32_bf16 v[80:83], v[140:143], v[156:159], v[80:83]
	v_mfma_f32_16x16x32_bf16 v[76:79], v[132:135], v[164:167], v[76:79]
	v_mfma_f32_16x16x32_bf16 v[72:75], v[140:143], v[164:167], v[72:75]
	v_mfma_f32_16x16x32_bf16 v[68:71], v[132:135], v[172:175], v[68:71]
	v_mfma_f32_16x16x32_bf16 v[64:67], v[140:143], v[172:175], v[64:67]
	v_mfma_f32_16x16x32_bf16 v[92:95], v[136:139], v[152:155], v[92:95]
	v_mfma_f32_16x16x32_bf16 v[88:91], v[144:147], v[152:155], v[88:91]
	v_mfma_f32_16x16x32_bf16 v[84:87], v[136:139], v[160:163], v[84:87]
	v_mfma_f32_16x16x32_bf16 v[80:83], v[144:147], v[160:163], v[80:83]
	v_mfma_f32_16x16x32_bf16 v[76:79], v[136:139], v[168:171], v[76:79]
	v_mfma_f32_16x16x32_bf16 v[72:75], v[144:147], v[168:171], v[72:75]
	v_mfma_f32_16x16x32_bf16 v[68:71], v[136:139], v[192:195], v[68:71]
	v_mfma_f32_16x16x32_bf16 v[64:67], v[144:147], v[192:195], v[64:67]
	s_barrier
	s_add_u32 s10, s66, 0x40000
	s_addc_u32 s11, s67, 0
	s_add_i32 s40, s40, s57
	s_mov_b32 m0, s40
	s_nop 0
	global_load_lds_dwordx4 v182, s[10:11]
	s_add_i32 m0, s40, 0x2000
	s_nop 0
	global_load_lds_dwordx4 v186, s[10:11]
	s_waitcnt vmcnt(6)
	s_barrier
; #define PG8_STAGE(bufoff, gbase, voff) do { _Pragma("unroll") for (int _i = 0; _i < 2; ++_i) \
;         __builtin_amdgcn_global_load_lds((const unsigned*)((const char*)(gbase) + (voff)[_i]), (LAS unsigned*)(lds + (bufoff) + ldsw + _i * 8192), 16, 0, 0); } while (0)
; #define PG8_LDA(dst, b, h) do { _Pragma("unroll") for (int m = 0; m < 4; ++m) _Pragma("unroll") for (int k = 0; k < 2; ++k) dst[m][k] = *(const LAS bf16x8*)(lds + PG8_SA(b, h) + aoff + m * 2048 + k * 1024); } while (0)
; #define PG8_LDB(dst, b, h) do { _Pragma("unroll") for (int n = 0; n < 2; ++n) _Pragma("unroll") for (int k = 0; k < 2; ++k) dst[n][k] = *(const LAS bf16x8*)(lds + PG8_SB(b, h) + boff + n * 2048 + k * 1024); } while (0)
; #define PG8_MMA(ai, bj, At, Bt) do { __builtin_amdgcn_s_setprio(1); _Pragma("unroll") for (int m = 0; m < 4; ++m) _Pragma("unroll") for (int n = 0; n < 2; ++n) _Pragma("unroll") for (int k = 0; k < 2; ++k) \
;         acc[ai][bj][m][n] = __builtin_amdgcn_mfma_f32_16x16x32_bf16(Bt[n][k], At[m][k], acc[ai][bj][m][n], 0, 0, 0); __builtin_amdgcn_s_setprio(0); } while (0)
; #define PG8_WAIT_V(n) asm volatile("s_waitcnt vmcnt(" #n ")" ::: "memory")
; #define PG8_WAIT_L(n) asm volatile("s_waitcnt lgkmcnt(" #n ")" ::: "memory")
; #define PG8_BAR __builtin_amdgcn_s_barrier()
; #define PG8_SCHED __builtin_amdgcn_sched_barrier(0)
; template <class Epi>
; __device__ __forceinline__ void gemm_phase(LAS unsigned char* lds, const Gemm g, const StaticOrder& S, const Epi& E) {
;     ...
;             PG8_WAIT_V(6); PG8_BAR; PG8_MMA(1, 1, At, B1); PG8_BAR;
;             PG8_LDB(B0, 1, 0); PG8_SCHED; PG8_LDA(At, 1, 0); PG8_STAGE(PG8_SA(0, 1), a2 + hstepA, voffA);
;             PG8_WAIT_L(8); PG8_BAR; PG8_WAIT_L(0); PG8_MMA(0, 0, At, B0); PG8_BAR; PG8_SCHED;
;             PG8_LDB(B1, 1, 1); PG8_STAGE(PG8_SB(1, 0), b3, voffB);
;             PG8_BAR; PG8_WAIT_L(0); PG8_MMA(0, 1, At, B1); PG8_BAR;
;             PG8_LDA(At, 1, 1); PG8_STAGE(PG8_SA(1, 0), a3, voffA);
;             PG8_BAR; PG8_WAIT_L(0); PG8_MMA(1, 0, At, B0); PG8_BAR; PG8_SCHED;
	v_mfma_f32_16x16x32_bf16 v[28:31], v[196:199], v[148:151], v[28:31]
	v_mfma_f32_16x16x32_bf16 v[24:27], v[204:207], v[148:151], v[24:27]
	v_mfma_f32_16x16x32_bf16 v[20:23], v[196:199], v[156:159], v[20:23]
	v_mfma_f32_16x16x32_bf16 v[16:19], v[204:207], v[156:159], v[16:19]
	v_mfma_f32_16x16x32_bf16 v[12:15], v[196:199], v[164:167], v[12:15]
	v_mfma_f32_16x16x32_bf16 v[8:11], v[204:207], v[164:167], v[8:11]
	v_mfma_f32_16x16x32_bf16 v[4:7], v[196:199], v[172:175], v[4:7]
	v_mfma_f32_16x16x32_bf16 v[0:3], v[204:207], v[172:175], v[0:3]
	v_mfma_f32_16x16x32_bf16 v[28:31], v[200:203], v[152:155], v[28:31]
	v_mfma_f32_16x16x32_bf16 v[24:27], v[208:211], v[152:155], v[24:27]
	v_mfma_f32_16x16x32_bf16 v[20:23], v[200:203], v[160:163], v[20:23]
	v_mfma_f32_16x16x32_bf16 v[16:19], v[208:211], v[160:163], v[16:19]
	v_mfma_f32_16x16x32_bf16 v[12:15], v[200:203], v[168:171], v[12:15]
	v_mfma_f32_16x16x32_bf16 v[8:11], v[208:211], v[168:171], v[8:11]
	v_mfma_f32_16x16x32_bf16 v[4:7], v[200:203], v[192:195], v[4:7]
	v_mfma_f32_16x16x32_bf16 v[0:3], v[208:211], v[192:195], v[0:3]
	s_add_i32 s40, 0, 0x18000
	v_add_u32_e32 v144, s40, v252
	s_barrier
	ds_read_b128 v[132:135], v144
	ds_read_b128 v[136:139], v144 offset:1024
	ds_read_b128 v[140:143], v144 offset:2048
	ds_read_b128 v[144:147], v144 offset:3072
	s_add_u32 s10, s68, s54
	s_addc_u32 s11, s69, 0
	s_mov_b32 m0, s4
	ds_read_b128 v[148:151], v241 offset:32768
	ds_read_b128 v[152:155], v241 offset:33792
	ds_read_b128 v[156:159], v241 offset:34816
	ds_read_b128 v[160:163], v241 offset:35840
	ds_read_b128 v[164:167], v241 offset:36864
	ds_read_b128 v[168:171], v241 offset:37888
	ds_read_b128 v[172:175], v241 offset:38912
	ds_read_b128 v[192:195], v241 offset:39936
	global_load_lds_dwordx4 v180, s[10:11]
	s_mov_b32 m0, s70
	s_nop 0
	global_load_lds_dwordx4 v184, s[10:11]
	s_waitcnt lgkmcnt(8)
	s_barrier
	s_waitcnt lgkmcnt(0)
	v_mfma_f32_16x16x32_bf16 v[124:127], v[132:135], v[148:151], v[124:127]
	v_mfma_f32_16x16x32_bf16 v[120:123], v[140:143], v[148:151], v[120:123]
	v_mfma_f32_16x16x32_bf16 v[116:119], v[132:135], v[156:159], v[116:119]
	v_mfma_f32_16x16x32_bf16 v[112:115], v[140:143], v[156:159], v[112:115]
	v_mfma_f32_16x16x32_bf16 v[108:111], v[132:135], v[164:167], v[108:111]
	v_mfma_f32_16x16x32_bf16 v[104:107], v[140:143], v[164:167], v[104:107]
	v_mfma_f32_16x16x32_bf16 v[100:103], v[132:135], v[172:175], v[100:103]
	v_mfma_f32_16x16x32_bf16 v[96:99], v[140:143], v[172:175], v[96:99]
	v_mfma_f32_16x16x32_bf16 v[124:127], v[136:139], v[152:155], v[124:127]
	v_mfma_f32_16x16x32_bf16 v[120:123], v[144:147], v[152:155], v[120:123]
	v_mfma_f32_16x16x32_bf16 v[116:119], v[136:139], v[160:163], v[116:119]
	v_mfma_f32_16x16x32_bf16 v[112:115], v[144:147], v[160:163], v[112:115]
	v_mfma_f32_16x16x32_bf16 v[108:111], v[136:139], v[168:171], v[108:111]
	v_mfma_f32_16x16x32_bf16 v[104:107], v[144:147], v[168:171], v[104:107]
	v_mfma_f32_16x16x32_bf16 v[100:103], v[136:139], v[192:195], v[100:103]
	v_mfma_f32_16x16x32_bf16 v[96:99], v[144:147], v[192:195], v[96:99]
	s_barrier
	s_add_i32 s41, 0, 0x1c000
	s_add_i32 s10, s40, s57
	v_add_u32_e32 v176, s41, v252
	s_add_u32 s100, s66, 0x80
	s_addc_u32 s101, s67, 0
	s_mov_b32 m0, s10
	ds_read_b128 v[196:199], v176
	ds_read_b128 v[200:203], v176 offset:1024
	ds_read_b128 v[204:207], v176 offset:2048
	ds_read_b128 v[208:211], v176 offset:3072
	global_load_lds_dwordx4 v182, s[100:101]
	s_add_i32 m0, s10, 0x2000
	s_nop 0
	global_load_lds_dwordx4 v186, s[100:101]
	s_barrier
	s_waitcnt lgkmcnt(0)
	v_mfma_f32_16x16x32_bf16 v[60:63], v[196:199], v[148:151], v[60:63]
	v_mfma_f32_16x16x32_bf16 v[56:59], v[204:207], v[148:151], v[56:59]
	v_mfma_f32_16x16x32_bf16 v[52:55], v[196:199], v[156:159], v[52:55]
	v_mfma_f32_16x16x32_bf16 v[48:51], v[204:207], v[156:159], v[48:51]
	v_mfma_f32_16x16x32_bf16 v[44:47], v[196:199], v[164:167], v[44:47]
	v_mfma_f32_16x16x32_bf16 v[40:43], v[204:207], v[164:167], v[40:43]
	v_mfma_f32_16x16x32_bf16 v[36:39], v[196:199], v[172:175], v[36:39]
	v_mfma_f32_16x16x32_bf16 v[32:35], v[204:207], v[172:175], v[32:35]
	v_mfma_f32_16x16x32_bf16 v[60:63], v[200:203], v[152:155], v[60:63]
	v_mfma_f32_16x16x32_bf16 v[56:59], v[208:211], v[152:155], v[56:59]
	v_mfma_f32_16x16x32_bf16 v[52:55], v[200:203], v[160:163], v[52:55]
	v_mfma_f32_16x16x32_bf16 v[48:51], v[208:211], v[160:163], v[48:51]
	v_mfma_f32_16x16x32_bf16 v[44:47], v[200:203], v[168:171], v[44:47]
	v_mfma_f32_16x16x32_bf16 v[40:43], v[208:211], v[168:171], v[40:43]
	v_mfma_f32_16x16x32_bf16 v[36:39], v[200:203], v[192:195], v[36:39]
	v_mfma_f32_16x16x32_bf16 v[32:35], v[208:211], v[192:195], v[32:35]
	s_mov_b32 m0, s6
	s_add_u32 s100, s68, 0x80
	s_addc_u32 s101, s69, 0
	s_barrier
	ds_read_b128 v[148:151], v241 offset:49152
	ds_read_b128 v[152:155], v241 offset:50176
	ds_read_b128 v[156:159], v241 offset:51200
	ds_read_b128 v[160:163], v241 offset:52224
	ds_read_b128 v[164:167], v241 offset:53248
	ds_read_b128 v[168:171], v241 offset:54272
	ds_read_b128 v[172:175], v241 offset:55296
	ds_read_b128 v[192:195], v241 offset:56320
	global_load_lds_dwordx4 v180, s[100:101]
	s_mov_b32 m0, s78
	s_nop 0
	global_load_lds_dwordx4 v184, s[100:101]
	s_barrier
; __device__ __forceinline__ float bf_lo(unsigned u) { return __uint_as_float(u << 16); }
; __device__ __forceinline__ float bf_hi(unsigned u) { return __uint_as_float(u & 0xffff0000u); }
; #define PG8_STAGE(bufoff, gbase, voff) do { _Pragma("unroll") for (int _i = 0; _i < 2; ++_i) \
;         __builtin_amdgcn_global_load_lds((const unsigned*)((const char*)(gbase) + (voff)[_i]), (LAS unsigned*)(lds + (bufoff) + ldsw + _i * 8192), 16, 0, 0); } while (0)
; #define PG8_MMA(ai, bj, At, Bt) do { __builtin_amdgcn_s_setprio(1); _Pragma("unroll") for (int m = 0; m < 4; ++m) _Pragma("unroll") for (int n = 0; n < 2; ++n) _Pragma("unroll") for (int k = 0; k < 2; ++k) \
;         acc[ai][bj][m][n] = __builtin_amdgcn_mfma_f32_16x16x32_bf16(Bt[n][k], At[m][k], acc[ai][bj][m][n], 0, 0, 0); __builtin_amdgcn_s_setprio(0); } while (0)
; #define PG8_WAIT_V(n) asm volatile("s_waitcnt vmcnt(" #n ")" ::: "memory")
; #define PG8_WAIT_L(n) asm volatile("s_waitcnt lgkmcnt(" #n ")" ::: "memory")
; #define PG8_BAR __builtin_amdgcn_s_barrier()
; template <class Epi>
; __device__ __forceinline__ void gemm_phase(LAS unsigned char* lds, const Gemm g, const StaticOrder& S, const Epi& E) {
;     ...
;             PG8_BAR; PG8_WAIT_L(0); PG8_MMA(1, 0, At, B0); PG8_BAR; PG8_SCHED;
;             PG8_STAGE(PG8_SB(1, 1), b3 + hstepB, voffB);
;             PG8_WAIT_V(6); PG8_BAR; PG8_MMA(1, 1, At, B1); PG8_BAR;
;         }
;         if (!lastpass) { E.mid(acc, cur, wr, wc, fr, fq); cA = nA; cB = nB; }
;     __device__ __forceinline__ void mid(f32x4 (&acc)[2][2][4][2], const pg8::Unit& u, int wr, int wc, int fr_in, int fq_in) const {
;         int fr = fr_in, fq = fq_in; asm volatile("" : "+v"(fr), "+v"(fq));
;         const int row0 = u.pm * 256 + wr * 64 + fr, col0 = u.pn * 256 + wc * 32 + 8 * fq;
; #pragma unroll
;         for (int i = 0; i < 16; ++i) { const int ai = i >> 3, m = (i >> 1) & 3, bj = i & 1; const int n = col0 + bj * 128;
;             const u32x4 gq = *(const u32x4*)(proj + (size_t)(row0 + ai * 128 + m * 16) * NC1 + C_MG + (n >> 7) * 256 + (n & 127));
;             acc[ai][bj][m][0][0] *= bf_lo(gq.x); acc[ai][bj][m][0][1] *= bf_hi(gq.x); acc[ai][bj][m][0][2] *= bf_lo(gq.y); acc[ai][bj][m][0][3] *= bf_hi(gq.y);
;             acc[ai][bj][m][1][0] *= bf_lo(gq.z); acc[ai][bj][m][1][1] *= bf_hi(gq.z); acc[ai][bj][m][1][2] *= bf_lo(gq.w); acc[ai][bj][m][1][3] *= bf_hi(gq.w); }
	s_waitcnt lgkmcnt(0)
	v_mfma_f32_16x16x32_bf16 v[92:95], v[132:135], v[148:151], v[92:95]
	v_mfma_f32_16x16x32_bf16 v[88:91], v[140:143], v[148:151], v[88:91]
	v_mfma_f32_16x16x32_bf16 v[84:87], v[132:135], v[156:159], v[84:87]
	v_mfma_f32_16x16x32_bf16 v[80:83], v[140:143], v[156:159], v[80:83]
	v_mfma_f32_16x16x32_bf16 v[76:79], v[132:135], v[164:167], v[76:79]
	v_mfma_f32_16x16x32_bf16 v[72:75], v[140:143], v[164:167], v[72:75]
	v_mfma_f32_16x16x32_bf16 v[68:71], v[132:135], v[172:175], v[68:71]
	v_mfma_f32_16x16x32_bf16 v[64:67], v[140:143], v[172:175], v[64:67]
	v_mfma_f32_16x16x32_bf16 v[92:95], v[136:139], v[152:155], v[92:95]
	v_mfma_f32_16x16x32_bf16 v[88:91], v[144:147], v[152:155], v[88:91]
	v_mfma_f32_16x16x32_bf16 v[84:87], v[136:139], v[160:163], v[84:87]
	v_mfma_f32_16x16x32_bf16 v[80:83], v[144:147], v[160:163], v[80:83]
	v_mfma_f32_16x16x32_bf16 v[76:79], v[136:139], v[168:171], v[76:79]
	v_mfma_f32_16x16x32_bf16 v[72:75], v[144:147], v[168:171], v[72:75]
	v_mfma_f32_16x16x32_bf16 v[68:71], v[136:139], v[192:195], v[68:71]
	v_mfma_f32_16x16x32_bf16 v[64:67], v[144:147], v[192:195], v[64:67]
	s_barrier
	s_add_u32 s10, s66, 0x40080
	s_addc_u32 s11, s67, 0
	s_add_i32 s40, s41, s57
	s_mov_b32 m0, s40
	s_nop 0
	global_load_lds_dwordx4 v182, s[10:11]
	s_add_i32 m0, s40, 0x2000
	s_nop 0
	global_load_lds_dwordx4 v186, s[10:11]
	s_waitcnt vmcnt(6)
	s_barrier
	v_mfma_f32_16x16x32_bf16 v[28:31], v[196:199], v[148:151], v[28:31]
	v_mfma_f32_16x16x32_bf16 v[24:27], v[204:207], v[148:151], v[24:27]
	v_mfma_f32_16x16x32_bf16 v[20:23], v[196:199], v[156:159], v[20:23]
	v_mfma_f32_16x16x32_bf16 v[16:19], v[204:207], v[156:159], v[16:19]
	v_mfma_f32_16x16x32_bf16 v[12:15], v[196:199], v[164:167], v[12:15]
	v_mfma_f32_16x16x32_bf16 v[8:11], v[204:207], v[164:167], v[8:11]
	v_mfma_f32_16x16x32_bf16 v[4:7], v[196:199], v[172:175], v[4:7]
	v_mfma_f32_16x16x32_bf16 v[0:3], v[204:207], v[172:175], v[0:3]
	v_mfma_f32_16x16x32_bf16 v[28:31], v[200:203], v[152:155], v[28:31]
	v_mfma_f32_16x16x32_bf16 v[24:27], v[208:211], v[152:155], v[24:27]
	v_mfma_f32_16x16x32_bf16 v[20:23], v[200:203], v[160:163], v[20:23]
	v_mfma_f32_16x16x32_bf16 v[16:19], v[208:211], v[160:163], v[16:19]
	v_mfma_f32_16x16x32_bf16 v[12:15], v[200:203], v[168:171], v[12:15]
	v_mfma_f32_16x16x32_bf16 v[8:11], v[208:211], v[168:171], v[8:11]
	v_mfma_f32_16x16x32_bf16 v[4:7], v[200:203], v[192:195], v[4:7]
	v_mfma_f32_16x16x32_bf16 v[0:3], v[208:211], v[192:195], v[0:3]
	s_add_i32 s77, s77, 2
	s_add_u32 s64, s64, 0x100
	s_addc_u32 s65, s65, 0
	s_cmp_gt_u32 s77, 13
	s_barrier
	s_cbranch_scc0 .LBB0_302
	s_add_u32 s64, vcc_lo, 0xffffff00
	s_addc_u32 s65, vcc_hi, -1
	s_and_b64 vcc, exec, s[62:63]
	s_cbranch_vccz .LBB0_300
	v_mov_b32_e32 v128, v251
	v_mov_b32_e32 v129, v179
	v_mov_b64_e32 v[130:131], s[98:99]
	v_lshl_add_u32 v128, v128, 3, s16
	v_lshlrev_b32_e32 v132, 1, v128
	v_add_u32_e32 v134, s15, v129
	v_and_b32_e32 v140, 0xffffff00, v132
	v_and_b32_e32 v135, 0x78, v128
	v_mad_i64_i32 v[128:129], s[10:11], v134, s22, v[130:131]
	v_ashrrev_i32_e32 v141, 31, v140
	v_lshl_add_u64 v[128:129], v[128:129], 0, s[34:35]
	v_lshlrev_b64 v[132:133], 1, v[140:141]
	v_lshlrev_b32_e32 v176, 1, v135
	v_lshl_add_u64 v[128:129], v[128:129], 0, v[132:133]
	v_lshl_add_u64 v[128:129], v[128:129], 0, v[176:177]
	s_mov_b64 s[64:65], s[44:45]
	s_mov_b64 s[46:47], s[0:1]
	s_mov_b64 s[100:101], 0x50000
	global_load_dwordx4 v[132:135], v[128:129], off
	global_load_dwordx4 v[136:139], v[128:129], off offset:512
	v_lshl_add_u64 v[130:131], v[128:129], 0, s[100:101]
	global_load_dwordx4 v[140:143], v[130:131], off
	global_load_dwordx4 v[144:147], v[130:131], off offset:512
	v_lshl_add_u64 v[130:131], v[130:131], 0, s[100:101]
	global_load_dwordx4 v[148:151], v[130:131], off
	global_load_dwordx4 v[152:155], v[130:131], off offset:512
	v_lshl_add_u64 v[130:131], v[130:131], 0, s[100:101]
	global_load_dwordx4 v[156:159], v[130:131], off
	global_load_dwordx4 v[160:163], v[130:131], off offset:512
	s_mov_b64 s[100:101], 0x280000
	v_lshl_add_u64 v[130:131], v[128:129], 0, s[100:101]
	s_mov_b64 s[100:101], 0x50000
	global_load_dwordx4 v[164:167], v[130:131], off
	global_load_dwordx4 v[168:171], v[130:131], off offset:512
	v_lshl_add_u64 v[130:131], v[130:131], 0, s[100:101]
	global_load_dwordx4 v[172:175], v[130:131], off
	global_load_dwordx4 v[192:195], v[130:131], off offset:512
	v_lshl_add_u64 v[130:131], v[130:131], 0, s[100:101]
	global_load_dwordx4 v[196:199], v[130:131], off
	global_load_dwordx4 v[200:203], v[130:131], off offset:512
	v_lshl_add_u64 v[130:131], v[130:131], 0, s[100:101]
	global_load_dwordx4 v[204:207], v[130:131], off
	global_load_dwordx4 v[208:211], v[130:131], off offset:512
	s_waitcnt vmcnt(15)
	v_lshlrev_b32_e32 v128, 16, v132
	v_and_b32_e32 v129, 0xffff0000, v132
	v_lshlrev_b32_e32 v130, 16, v133
	v_and_b32_e32 v131, 0xffff0000, v133
	v_pk_mul_f32 v[124:125], v[124:125], v[128:129]
	v_pk_mul_f32 v[126:127], v[126:127], v[130:131]
	v_lshlrev_b32_e32 v128, 16, v134
	v_and_b32_e32 v129, 0xffff0000, v134
	v_lshlrev_b32_e32 v130, 16, v135
	v_and_b32_e32 v131, 0xffff0000, v135
	v_pk_mul_f32 v[120:121], v[120:121], v[128:129]
	v_pk_mul_f32 v[122:123], v[122:123], v[130:131]
	s_waitcnt vmcnt(14)
	v_lshlrev_b32_e32 v128, 16, v136
	v_and_b32_e32 v129, 0xffff0000, v136
	v_lshlrev_b32_e32 v130, 16, v137
	v_and_b32_e32 v131, 0xffff0000, v137
	v_pk_mul_f32 v[60:61], v[60:61], v[128:129]
	v_pk_mul_f32 v[62:63], v[62:63], v[130:131]
	v_lshlrev_b32_e32 v128, 16, v138
	v_and_b32_e32 v129, 0xffff0000, v138
	v_lshlrev_b32_e32 v130, 16, v139
	v_and_b32_e32 v131, 0xffff0000, v139
	v_pk_mul_f32 v[56:57], v[56:57], v[128:129]
	v_pk_mul_f32 v[58:59], v[58:59], v[130:131]
	s_waitcnt vmcnt(13)
; __device__ __forceinline__ float bf_lo(unsigned u) { return __uint_as_float(u << 16); }
; __device__ __forceinline__ float bf_hi(unsigned u) { return __uint_as_float(u & 0xffff0000u); }
;     __device__ __forceinline__ void mid(f32x4 (&acc)[2][2][4][2], const pg8::Unit& u, int wr, int wc, int fr_in, int fq_in) const {
;     ...
;         for (int i = 0; i < 16; ++i) { const int ai = i >> 3, m = (i >> 1) & 3, bj = i & 1; const int n = col0 + bj * 128;
;             const u32x4 gq = *(const u32x4*)(proj + (size_t)(row0 + ai * 128 + m * 16) * NC1 + C_MG + (n >> 7) * 256 + (n & 127));
;             acc[ai][bj][m][0][0] *= bf_lo(gq.x); acc[ai][bj][m][0][1] *= bf_hi(gq.x); acc[ai][bj][m][0][2] *= bf_lo(gq.y); acc[ai][bj][m][0][3] *= bf_hi(gq.y);
;             acc[ai][bj][m][1][0] *= bf_lo(gq.z); acc[ai][bj][m][1][1] *= bf_hi(gq.z); acc[ai][bj][m][1][2] *= bf_lo(gq.w); acc[ai][bj][m][1][3] *= bf_hi(gq.w); }
	v_lshlrev_b32_e32 v128, 16, v140
	v_and_b32_e32 v129, 0xffff0000, v140
	v_lshlrev_b32_e32 v130, 16, v141
	v_and_b32_e32 v131, 0xffff0000, v141
	v_pk_mul_f32 v[116:117], v[116:117], v[128:129]
	v_pk_mul_f32 v[118:119], v[118:119], v[130:131]
	v_lshlrev_b32_e32 v128, 16, v142
	v_and_b32_e32 v129, 0xffff0000, v142
	v_lshlrev_b32_e32 v130, 16, v143
	v_and_b32_e32 v131, 0xffff0000, v143
	v_pk_mul_f32 v[112:113], v[112:113], v[128:129]
	v_pk_mul_f32 v[114:115], v[114:115], v[130:131]
	s_waitcnt vmcnt(12)
	v_lshlrev_b32_e32 v128, 16, v144
	v_and_b32_e32 v129, 0xffff0000, v144
	v_lshlrev_b32_e32 v130, 16, v145
	v_and_b32_e32 v131, 0xffff0000, v145
	v_pk_mul_f32 v[52:53], v[52:53], v[128:129]
	v_pk_mul_f32 v[54:55], v[54:55], v[130:131]
	v_lshlrev_b32_e32 v128, 16, v146
	v_and_b32_e32 v129, 0xffff0000, v146
	v_lshlrev_b32_e32 v130, 16, v147
	v_and_b32_e32 v131, 0xffff0000, v147
	v_pk_mul_f32 v[48:49], v[48:49], v[128:129]
	v_pk_mul_f32 v[50:51], v[50:51], v[130:131]
	s_waitcnt vmcnt(11)
	v_lshlrev_b32_e32 v128, 16, v148
	v_and_b32_e32 v129, 0xffff0000, v148
	v_lshlrev_b32_e32 v130, 16, v149
	v_and_b32_e32 v131, 0xffff0000, v149
	v_pk_mul_f32 v[108:109], v[108:109], v[128:129]
	v_pk_mul_f32 v[110:111], v[110:111], v[130:131]
	v_lshlrev_b32_e32 v128, 16, v150
	v_and_b32_e32 v129, 0xffff0000, v150
	v_lshlrev_b32_e32 v130, 16, v151
	v_and_b32_e32 v131, 0xffff0000, v151
	v_pk_mul_f32 v[104:105], v[104:105], v[128:129]
	v_pk_mul_f32 v[106:107], v[106:107], v[130:131]
	s_waitcnt vmcnt(10)
	v_lshlrev_b32_e32 v128, 16, v152
	v_and_b32_e32 v129, 0xffff0000, v152
	v_lshlrev_b32_e32 v130, 16, v153
	v_and_b32_e32 v131, 0xffff0000, v153
	v_pk_mul_f32 v[44:45], v[44:45], v[128:129]
	v_pk_mul_f32 v[46:47], v[46:47], v[130:131]
	v_lshlrev_b32_e32 v128, 16, v154
	v_and_b32_e32 v129, 0xffff0000, v154
	v_lshlrev_b32_e32 v130, 16, v155
	v_and_b32_e32 v131, 0xffff0000, v155
	v_pk_mul_f32 v[40:41], v[40:41], v[128:129]
	v_pk_mul_f32 v[42:43], v[42:43], v[130:131]
	s_waitcnt vmcnt(9)
	v_lshlrev_b32_e32 v128, 16, v156
	v_and_b32_e32 v129, 0xffff0000, v156
	v_lshlrev_b32_e32 v130, 16, v157
	v_and_b32_e32 v131, 0xffff0000, v157
	v_pk_mul_f32 v[100:101], v[100:101], v[128:129]
	v_pk_mul_f32 v[102:103], v[102:103], v[130:131]
	v_lshlrev_b32_e32 v128, 16, v158
	v_and_b32_e32 v129, 0xffff0000, v158
	v_lshlrev_b32_e32 v130, 16, v159
	v_and_b32_e32 v131, 0xffff0000, v159
	v_pk_mul_f32 v[96:97], v[96:97], v[128:129]
	v_pk_mul_f32 v[98:99], v[98:99], v[130:131]
	s_waitcnt vmcnt(8)
	v_lshlrev_b32_e32 v128, 16, v160
	v_and_b32_e32 v129, 0xffff0000, v160
	v_lshlrev_b32_e32 v130, 16, v161
	v_and_b32_e32 v131, 0xffff0000, v161
	v_pk_mul_f32 v[36:37], v[36:37], v[128:129]
	v_pk_mul_f32 v[38:39], v[38:39], v[130:131]
	v_lshlrev_b32_e32 v128, 16, v162
	v_and_b32_e32 v129, 0xffff0000, v162
	v_lshlrev_b32_e32 v130, 16, v163
	v_and_b32_e32 v131, 0xffff0000, v163
	v_pk_mul_f32 v[32:33], v[32:33], v[128:129]
	v_pk_mul_f32 v[34:35], v[34:35], v[130:131]
	s_waitcnt vmcnt(7)
	v_lshlrev_b32_e32 v128, 16, v164
	v_and_b32_e32 v129, 0xffff0000, v164
	v_lshlrev_b32_e32 v130, 16, v165
	v_and_b32_e32 v131, 0xffff0000, v165
	v_pk_mul_f32 v[92:93], v[92:93], v[128:129]
	v_pk_mul_f32 v[94:95], v[94:95], v[130:131]
	v_lshlrev_b32_e32 v128, 16, v166
	v_and_b32_e32 v129, 0xffff0000, v166
	v_lshlrev_b32_e32 v130, 16, v167
	v_and_b32_e32 v131, 0xffff0000, v167
	v_pk_mul_f32 v[88:89], v[88:89], v[128:129]
	v_pk_mul_f32 v[90:91], v[90:91], v[130:131]
	s_waitcnt vmcnt(6)
	v_lshlrev_b32_e32 v128, 16, v168
	v_and_b32_e32 v129, 0xffff0000, v168
	v_lshlrev_b32_e32 v130, 16, v169
	v_and_b32_e32 v131, 0xffff0000, v169
	v_pk_mul_f32 v[28:29], v[28:29], v[128:129]
	v_pk_mul_f32 v[30:31], v[30:31], v[130:131]
	v_lshlrev_b32_e32 v128, 16, v170
	v_and_b32_e32 v129, 0xffff0000, v170
	v_lshlrev_b32_e32 v130, 16, v171
	v_and_b32_e32 v131, 0xffff0000, v171
	v_pk_mul_f32 v[24:25], v[24:25], v[128:129]
	v_pk_mul_f32 v[26:27], v[26:27], v[130:131]
	s_waitcnt vmcnt(5)
	v_lshlrev_b32_e32 v128, 16, v172
	v_and_b32_e32 v129, 0xffff0000, v172
	v_lshlrev_b32_e32 v130, 16, v173
	v_and_b32_e32 v131, 0xffff0000, v173
	v_pk_mul_f32 v[84:85], v[84:85], v[128:129]
	v_pk_mul_f32 v[86:87], v[86:87], v[130:131]
	v_lshlrev_b32_e32 v128, 16, v174
	v_and_b32_e32 v129, 0xffff0000, v174
	v_lshlrev_b32_e32 v130, 16, v175
	v_and_b32_e32 v131, 0xffff0000, v175
	v_pk_mul_f32 v[80:81], v[80:81], v[128:129]
	v_pk_mul_f32 v[82:83], v[82:83], v[130:131]
	s_waitcnt vmcnt(4)
	v_lshlrev_b32_e32 v128, 16, v192
	v_and_b32_e32 v129, 0xffff0000, v192
	v_lshlrev_b32_e32 v130, 16, v193
	v_and_b32_e32 v131, 0xffff0000, v193
	v_pk_mul_f32 v[20:21], v[20:21], v[128:129]
	v_pk_mul_f32 v[22:23], v[22:23], v[130:131]
	v_lshlrev_b32_e32 v128, 16, v194
	v_and_b32_e32 v129, 0xffff0000, v194
	v_lshlrev_b32_e32 v130, 16, v195
	v_and_b32_e32 v131, 0xffff0000, v195
	v_pk_mul_f32 v[16:17], v[16:17], v[128:129]
	v_pk_mul_f32 v[18:19], v[18:19], v[130:131]
	s_waitcnt vmcnt(3)
	v_lshlrev_b32_e32 v128, 16, v196
	v_and_b32_e32 v129, 0xffff0000, v196
	v_lshlrev_b32_e32 v130, 16, v197
	v_and_b32_e32 v131, 0xffff0000, v197
	v_pk_mul_f32 v[76:77], v[76:77], v[128:129]
	v_pk_mul_f32 v[78:79], v[78:79], v[130:131]
	v_lshlrev_b32_e32 v128, 16, v198
	v_and_b32_e32 v129, 0xffff0000, v198
	v_lshlrev_b32_e32 v130, 16, v199
	v_and_b32_e32 v131, 0xffff0000, v199
	v_pk_mul_f32 v[72:73], v[72:73], v[128:129]
	v_pk_mul_f32 v[74:75], v[74:75], v[130:131]
	s_waitcnt vmcnt(2)
	v_lshlrev_b32_e32 v128, 16, v200
	v_and_b32_e32 v129, 0xffff0000, v200
	v_lshlrev_b32_e32 v130, 16, v201
	v_and_b32_e32 v131, 0xffff0000, v201
	v_pk_mul_f32 v[12:13], v[12:13], v[128:129]
	v_pk_mul_f32 v[14:15], v[14:15], v[130:131]
	v_lshlrev_b32_e32 v128, 16, v202
	v_and_b32_e32 v129, 0xffff0000, v202
	v_lshlrev_b32_e32 v130, 16, v203
	v_and_b32_e32 v131, 0xffff0000, v203
	v_pk_mul_f32 v[8:9], v[8:9], v[128:129]
	v_pk_mul_f32 v[10:11], v[10:11], v[130:131]
	s_waitcnt vmcnt(1)
	v_lshlrev_b32_e32 v128, 16, v204
	v_and_b32_e32 v129, 0xffff0000, v204
	v_lshlrev_b32_e32 v130, 16, v205
	v_and_b32_e32 v131, 0xffff0000, v205
	v_pk_mul_f32 v[68:69], v[68:69], v[128:129]
	v_pk_mul_f32 v[70:71], v[70:71], v[130:131]
	v_lshlrev_b32_e32 v128, 16, v206
	v_and_b32_e32 v129, 0xffff0000, v206
	v_lshlrev_b32_e32 v130, 16, v207
	v_and_b32_e32 v131, 0xffff0000, v207
	v_pk_mul_f32 v[64:65], v[64:65], v[128:129]
	v_pk_mul_f32 v[66:67], v[66:67], v[130:131]
	s_waitcnt vmcnt(0)
	v_lshlrev_b32_e32 v128, 16, v208
	v_and_b32_e32 v129, 0xffff0000, v208
	v_lshlrev_b32_e32 v130, 16, v209
	v_and_b32_e32 v131, 0xffff0000, v209
	v_pk_mul_f32 v[4:5], v[4:5], v[128:129]
	v_pk_mul_f32 v[6:7], v[6:7], v[130:131]
	v_lshlrev_b32_e32 v128, 16, v210
	v_and_b32_e32 v129, 0xffff0000, v210
	v_lshlrev_b32_e32 v130, 16, v211
	v_and_b32_e32 v131, 0xffff0000, v211
	v_pk_mul_f32 v[0:1], v[0:1], v[128:129]
	v_pk_mul_f32 v[2:3], v[2:3], v[130:131]
	s_branch .LBB0_300
